# k11 + one extra LDS drain between the B0 and B1 fragment reads in proj/gate_up SP1 load segments (4+drain+4+drain+8), byte-neutral
# speedup vs baseline: 1.0135x; 1.0032x over previous
.LBB0_165:
	s_mov_b32 s98, 0x10000
	ds_read_b128 v[148:151], v250
	ds_read_b128 v[152:155], v250 offset:1024
	ds_read_b128 v[156:159], v250 offset:2048
	ds_read_b128 v[160:163], v250 offset:3072
	s_waitcnt lgkmcnt(0)
	s_nop 0
	ds_read_b128 v[132:135], v250 offset:16384
	ds_read_b128 v[136:139], v250 offset:17408
	ds_read_b128 v[140:143], v250 offset:18432
	ds_read_b128 v[144:147], v250 offset:19456
	v_lshl_add_u64 v[2:3], v[224:225], 0, s[0:1]
	s_add_i32 m0, s77, 0xc000
	s_waitcnt lgkmcnt(0)
	ds_read_b128 v[176:179], v246
	ds_read_b128 v[192:195], v246 offset:1024
	ds_read_b128 v[172:175], v246 offset:2048
	ds_read_b128 v[188:191], v246 offset:3072
	ds_read_b128 v[168:171], v246 offset:4096
	ds_read_b128 v[184:187], v246 offset:5120
	ds_read_b128 v[164:167], v246 offset:6144
	ds_read_b128 v[180:183], v246 offset:7168
	global_load_lds_dwordx4 v[2:3], off
	v_lshl_add_u64 v[2:3], v[222:223], 0, s[0:1]
	s_add_i32 m0, s77, 0xe000
	s_nop 0
	global_load_lds_dwordx4 v[2:3], off
	s_waitcnt vmcnt(8)
	s_waitcnt lgkmcnt(0)
	s_barrier
	s_setprio 1
	s_waitcnt lgkmcnt(0)
	v_mfma_f32_16x16x32_bf16 v[128:131], v[148:151], v[176:179], v[128:131]
	v_mfma_f32_16x16x32_bf16 v[124:127], v[156:159], v[176:179], v[124:127]
	v_mfma_f32_16x16x32_bf16 v[112:115], v[148:151], v[172:175], v[112:115]
	v_mfma_f32_16x16x32_bf16 v[108:111], v[156:159], v[172:175], v[108:111]
	v_mfma_f32_16x16x32_bf16 v[96:99], v[148:151], v[168:171], v[96:99]
	v_mfma_f32_16x16x32_bf16 v[92:95], v[156:159], v[168:171], v[92:95]
	v_mfma_f32_16x16x32_bf16 v[80:83], v[148:151], v[164:167], v[80:83]
	v_mfma_f32_16x16x32_bf16 v[76:79], v[156:159], v[164:167], v[76:79]
	v_mfma_f32_16x16x32_bf16 v[128:131], v[152:155], v[192:195], v[128:131]
	v_mfma_f32_16x16x32_bf16 v[124:127], v[160:163], v[192:195], v[124:127]
	v_mfma_f32_16x16x32_bf16 v[112:115], v[152:155], v[188:191], v[112:115]
	v_mfma_f32_16x16x32_bf16 v[108:111], v[160:163], v[188:191], v[108:111]
	v_mfma_f32_16x16x32_bf16 v[96:99], v[152:155], v[184:187], v[96:99]
	v_mfma_f32_16x16x32_bf16 v[92:95], v[160:163], v[184:187], v[92:95]
	v_mfma_f32_16x16x32_bf16 v[80:83], v[152:155], v[180:183], v[80:83]
	v_mfma_f32_16x16x32_bf16 v[76:79], v[160:163], v[180:183], v[76:79]
	s_setprio 0
	s_setprio 1
	v_mfma_f32_16x16x32_bf16 v[120:123], v[132:135], v[176:179], v[120:123]
	v_mfma_f32_16x16x32_bf16 v[116:119], v[140:143], v[176:179], v[116:119]
	v_mfma_f32_16x16x32_bf16 v[104:107], v[132:135], v[172:175], v[104:107]
	v_mfma_f32_16x16x32_bf16 v[100:103], v[140:143], v[172:175], v[100:103]
	v_mfma_f32_16x16x32_bf16 v[88:91], v[132:135], v[168:171], v[88:91]
	v_mfma_f32_16x16x32_bf16 v[84:87], v[140:143], v[168:171], v[84:87]
	v_mfma_f32_16x16x32_bf16 v[72:75], v[132:135], v[164:167], v[72:75]
	v_mfma_f32_16x16x32_bf16 v[68:71], v[140:143], v[164:167], v[68:71]
	v_mfma_f32_16x16x32_bf16 v[120:123], v[136:139], v[192:195], v[120:123]
	v_mfma_f32_16x16x32_bf16 v[116:119], v[144:147], v[192:195], v[116:119]
	v_mfma_f32_16x16x32_bf16 v[104:107], v[136:139], v[188:191], v[104:107]
	v_mfma_f32_16x16x32_bf16 v[100:103], v[144:147], v[188:191], v[100:103]
	v_mfma_f32_16x16x32_bf16 v[88:91], v[136:139], v[184:187], v[88:91]
	v_mfma_f32_16x16x32_bf16 v[84:87], v[144:147], v[184:187], v[84:87]
	v_mfma_f32_16x16x32_bf16 v[72:75], v[136:139], v[180:183], v[72:75]
	v_mfma_f32_16x16x32_bf16 v[68:71], v[144:147], v[180:183], v[68:71]
	s_setprio 0
	s_barrier
	v_cndmask_b32_e64 v1, 0, 1, s[20:21]
	v_cmp_ne_u32_e64 s[44:45], 1, v1
	s_andn2_b64 vcc, exec, s[20:21]
	s_cbranch_vccnz .LBB0_167
	ds_read_b128 v[176:179], v246 offset:16384
	ds_read_b128 v[192:195], v246 offset:17408
	ds_read_b128 v[172:175], v246 offset:18432
	ds_read_b128 v[188:191], v246 offset:19456
	ds_read_b128 v[168:171], v246 offset:20480
	ds_read_b128 v[184:187], v246 offset:21504
	ds_read_b128 v[164:167], v246 offset:22528
	ds_read_b128 v[180:183], v246 offset:23552

.LBB0_169:
	s_barrier
	s_mov_b32 s98, 0x18000
	ds_read_b128 v[148:151], v250 offset:32768
	ds_read_b128 v[152:155], v250 offset:33792
	ds_read_b128 v[156:159], v250 offset:34816
	ds_read_b128 v[160:163], v250 offset:35840
	s_waitcnt lgkmcnt(0)
	s_nop 0
	ds_read_b128 v[132:135], v250 offset:49152
	ds_read_b128 v[136:139], v250 offset:50176
	ds_read_b128 v[140:143], v250 offset:51200
	ds_read_b128 v[144:147], v250 offset:52224
	s_and_b64 s[26:27], s[42:43], s[26:27]
	s_and_b64 s[26:27], s[26:27], exec
	s_cselect_b32 s26, s52, s50
	s_cselect_b32 s27, 0, s51
	s_add_u32 s26, s66, s26
	s_addc_u32 s27, s67, s27
	s_mov_b32 m0, s85
	v_lshl_add_u64 v[196:197], s[26:27], 0, v[208:209]
	s_waitcnt lgkmcnt(0)
	ds_read_b128 v[176:179], v246 offset:32768
	ds_read_b128 v[192:195], v246 offset:33792
	ds_read_b128 v[172:175], v246 offset:34816
	ds_read_b128 v[188:191], v246 offset:35840
	ds_read_b128 v[168:171], v246 offset:36864
	ds_read_b128 v[184:187], v246 offset:37888
	ds_read_b128 v[164:167], v246 offset:38912
	ds_read_b128 v[180:183], v246 offset:39936
	global_load_lds_dwordx4 v[196:197], off
	v_lshl_add_u64 v[196:197], s[26:27], 0, v[212:213]
	s_mov_b32 m0, s86
	s_nop 0
	global_load_lds_dwordx4 v[196:197], off
	s_waitcnt vmcnt(8)
	s_waitcnt lgkmcnt(0)
	s_barrier
	s_setprio 1
	s_waitcnt lgkmcnt(0)
	v_mfma_f32_16x16x32_bf16 v[128:131], v[148:151], v[176:179], v[128:131]
	v_mfma_f32_16x16x32_bf16 v[124:127], v[156:159], v[176:179], v[124:127]
	v_mfma_f32_16x16x32_bf16 v[112:115], v[148:151], v[172:175], v[112:115]
	v_mfma_f32_16x16x32_bf16 v[108:111], v[156:159], v[172:175], v[108:111]
	v_mfma_f32_16x16x32_bf16 v[96:99], v[148:151], v[168:171], v[96:99]
	v_mfma_f32_16x16x32_bf16 v[92:95], v[156:159], v[168:171], v[92:95]
	v_mfma_f32_16x16x32_bf16 v[80:83], v[148:151], v[164:167], v[80:83]
	v_mfma_f32_16x16x32_bf16 v[76:79], v[156:159], v[164:167], v[76:79]
	v_mfma_f32_16x16x32_bf16 v[128:131], v[152:155], v[192:195], v[128:131]
	v_mfma_f32_16x16x32_bf16 v[124:127], v[160:163], v[192:195], v[124:127]
	v_mfma_f32_16x16x32_bf16 v[112:115], v[152:155], v[188:191], v[112:115]
	v_mfma_f32_16x16x32_bf16 v[108:111], v[160:163], v[188:191], v[108:111]
	v_mfma_f32_16x16x32_bf16 v[96:99], v[152:155], v[184:187], v[96:99]
	v_mfma_f32_16x16x32_bf16 v[92:95], v[160:163], v[184:187], v[92:95]
	v_mfma_f32_16x16x32_bf16 v[80:83], v[152:155], v[180:183], v[80:83]
	v_mfma_f32_16x16x32_bf16 v[76:79], v[160:163], v[180:183], v[76:79]
	s_setprio 0
	s_setprio 1
	v_mfma_f32_16x16x32_bf16 v[120:123], v[132:135], v[176:179], v[120:123]
	v_mfma_f32_16x16x32_bf16 v[116:119], v[140:143], v[176:179], v[116:119]
	v_mfma_f32_16x16x32_bf16 v[104:107], v[132:135], v[172:175], v[104:107]
	v_mfma_f32_16x16x32_bf16 v[100:103], v[140:143], v[172:175], v[100:103]
	v_mfma_f32_16x16x32_bf16 v[88:91], v[132:135], v[168:171], v[88:91]
	v_mfma_f32_16x16x32_bf16 v[84:87], v[140:143], v[168:171], v[84:87]
	v_mfma_f32_16x16x32_bf16 v[72:75], v[132:135], v[164:167], v[72:75]
	v_mfma_f32_16x16x32_bf16 v[68:71], v[140:143], v[164:167], v[68:71]
	v_mfma_f32_16x16x32_bf16 v[120:123], v[136:139], v[192:195], v[120:123]
	v_mfma_f32_16x16x32_bf16 v[116:119], v[144:147], v[192:195], v[116:119]
	v_mfma_f32_16x16x32_bf16 v[104:107], v[136:139], v[188:191], v[104:107]
	v_mfma_f32_16x16x32_bf16 v[100:103], v[144:147], v[188:191], v[100:103]
	v_mfma_f32_16x16x32_bf16 v[88:91], v[136:139], v[184:187], v[88:91]
	v_mfma_f32_16x16x32_bf16 v[84:87], v[144:147], v[184:187], v[84:87]
	v_mfma_f32_16x16x32_bf16 v[72:75], v[136:139], v[180:183], v[72:75]
	v_mfma_f32_16x16x32_bf16 v[68:71], v[144:147], v[180:183], v[68:71]
	s_setprio 0
	s_barrier
	s_and_b64 vcc, exec, s[44:45]
	s_cbranch_vccnz .LBB0_171
	ds_read_b128 v[176:179], v246 offset:49152
	ds_read_b128 v[192:195], v246 offset:50176
	ds_read_b128 v[172:175], v246 offset:51200
	ds_read_b128 v[188:191], v246 offset:52224
	ds_read_b128 v[168:171], v246 offset:53248
	ds_read_b128 v[184:187], v246 offset:54272
	ds_read_b128 v[164:167], v246 offset:55296
	ds_read_b128 v[180:183], v246 offset:56320

.LBB0_681:
	s_mov_b32 s98, 0x10000
	ds_read_b128 v[148:151], v250
	ds_read_b128 v[152:155], v250 offset:1024
	ds_read_b128 v[156:159], v250 offset:2048
	ds_read_b128 v[160:163], v250 offset:3072
	s_waitcnt lgkmcnt(0)
	s_nop 0
	ds_read_b128 v[132:135], v250 offset:16384
	ds_read_b128 v[136:139], v250 offset:17408
	ds_read_b128 v[140:143], v250 offset:18432
	ds_read_b128 v[144:147], v250 offset:19456
	v_lshl_add_u64 v[2:3], v[222:223], 0, s[0:1]
	s_add_i32 m0, s31, 0xc000
	s_waitcnt lgkmcnt(0)
	ds_read_b128 v[176:179], v242
	ds_read_b128 v[192:195], v242 offset:1024
	ds_read_b128 v[172:175], v242 offset:2048
	ds_read_b128 v[188:191], v242 offset:3072
	ds_read_b128 v[168:171], v242 offset:4096
	ds_read_b128 v[184:187], v242 offset:5120
	ds_read_b128 v[164:167], v242 offset:6144
	ds_read_b128 v[180:183], v242 offset:7168
	global_load_lds_dwordx4 v[2:3], off
	v_lshl_add_u64 v[2:3], v[220:221], 0, s[0:1]
	s_add_i32 m0, s31, 0xe000
	s_nop 0
	global_load_lds_dwordx4 v[2:3], off
	s_waitcnt vmcnt(8)
	s_waitcnt lgkmcnt(0)
	s_barrier
	s_setprio 1
	s_waitcnt lgkmcnt(0)
	v_mfma_f32_16x16x32_bf16 v[128:131], v[148:151], v[176:179], v[128:131]
	v_mfma_f32_16x16x32_bf16 v[124:127], v[156:159], v[176:179], v[124:127]
	v_mfma_f32_16x16x32_bf16 v[112:115], v[148:151], v[172:175], v[112:115]
	v_mfma_f32_16x16x32_bf16 v[108:111], v[156:159], v[172:175], v[108:111]
	v_mfma_f32_16x16x32_bf16 v[96:99], v[148:151], v[168:171], v[96:99]
	v_mfma_f32_16x16x32_bf16 v[92:95], v[156:159], v[168:171], v[92:95]
	v_mfma_f32_16x16x32_bf16 v[80:83], v[148:151], v[164:167], v[80:83]
	v_mfma_f32_16x16x32_bf16 v[76:79], v[156:159], v[164:167], v[76:79]
	v_mfma_f32_16x16x32_bf16 v[128:131], v[152:155], v[192:195], v[128:131]
	v_mfma_f32_16x16x32_bf16 v[124:127], v[160:163], v[192:195], v[124:127]
	v_mfma_f32_16x16x32_bf16 v[112:115], v[152:155], v[188:191], v[112:115]
	v_mfma_f32_16x16x32_bf16 v[108:111], v[160:163], v[188:191], v[108:111]
	v_mfma_f32_16x16x32_bf16 v[96:99], v[152:155], v[184:187], v[96:99]
	v_mfma_f32_16x16x32_bf16 v[92:95], v[160:163], v[184:187], v[92:95]
	v_mfma_f32_16x16x32_bf16 v[80:83], v[152:155], v[180:183], v[80:83]
	v_mfma_f32_16x16x32_bf16 v[76:79], v[160:163], v[180:183], v[76:79]
	s_setprio 0
	s_setprio 1
	v_mfma_f32_16x16x32_bf16 v[120:123], v[132:135], v[176:179], v[120:123]
	v_mfma_f32_16x16x32_bf16 v[116:119], v[140:143], v[176:179], v[116:119]
	v_mfma_f32_16x16x32_bf16 v[104:107], v[132:135], v[172:175], v[104:107]
	v_mfma_f32_16x16x32_bf16 v[100:103], v[140:143], v[172:175], v[100:103]
	v_mfma_f32_16x16x32_bf16 v[88:91], v[132:135], v[168:171], v[88:91]
	v_mfma_f32_16x16x32_bf16 v[84:87], v[140:143], v[168:171], v[84:87]
	v_mfma_f32_16x16x32_bf16 v[72:75], v[132:135], v[164:167], v[72:75]
	v_mfma_f32_16x16x32_bf16 v[68:71], v[140:143], v[164:167], v[68:71]
	v_mfma_f32_16x16x32_bf16 v[120:123], v[136:139], v[192:195], v[120:123]
	v_mfma_f32_16x16x32_bf16 v[116:119], v[144:147], v[192:195], v[116:119]
	v_mfma_f32_16x16x32_bf16 v[104:107], v[136:139], v[188:191], v[104:107]
	v_mfma_f32_16x16x32_bf16 v[100:103], v[144:147], v[188:191], v[100:103]
	v_mfma_f32_16x16x32_bf16 v[88:91], v[136:139], v[184:187], v[88:91]
	v_mfma_f32_16x16x32_bf16 v[84:87], v[144:147], v[184:187], v[84:87]
	v_mfma_f32_16x16x32_bf16 v[72:75], v[136:139], v[180:183], v[72:75]
	v_mfma_f32_16x16x32_bf16 v[68:71], v[144:147], v[180:183], v[68:71]
	s_setprio 0
	s_barrier
	v_cndmask_b32_e64 v1, 0, 1, s[14:15]
	v_cmp_ne_u32_e64 s[40:41], 1, v1
	s_andn2_b64 vcc, exec, s[14:15]
	s_cbranch_vccnz .LBB0_683
	ds_read_b128 v[176:179], v242 offset:16384
	ds_read_b128 v[192:195], v242 offset:17408
	ds_read_b128 v[172:175], v242 offset:18432
	ds_read_b128 v[188:191], v242 offset:19456
	ds_read_b128 v[168:171], v242 offset:20480
	ds_read_b128 v[184:187], v242 offset:21504
	ds_read_b128 v[164:167], v242 offset:22528
	ds_read_b128 v[180:183], v242 offset:23552

.LBB0_685:
	s_barrier
	s_mov_b32 s98, 0x18000
	ds_read_b128 v[148:151], v250 offset:32768
	ds_read_b128 v[152:155], v250 offset:33792
	ds_read_b128 v[156:159], v250 offset:34816
	ds_read_b128 v[160:163], v250 offset:35840
	s_waitcnt lgkmcnt(0)
	s_nop 0
	ds_read_b128 v[132:135], v250 offset:49152
	ds_read_b128 v[136:139], v250 offset:50176
	ds_read_b128 v[140:143], v250 offset:51200
	ds_read_b128 v[144:147], v250 offset:52224
	s_and_b64 s[26:27], s[38:39], s[26:27]
	s_and_b64 s[26:27], s[26:27], exec
	s_cselect_b32 s27, s52, s12
	s_cselect_b32 s26, 0, s13
	s_add_u32 s20, s20, s27
	s_addc_u32 s21, s21, s26
	s_mov_b32 m0, s51
	v_lshl_add_u64 v[196:197], s[20:21], 0, v[214:215]
	s_waitcnt lgkmcnt(0)
	ds_read_b128 v[176:179], v242 offset:32768
	ds_read_b128 v[192:195], v242 offset:33792
	ds_read_b128 v[172:175], v242 offset:34816
	ds_read_b128 v[188:191], v242 offset:35840
	ds_read_b128 v[168:171], v242 offset:36864
	ds_read_b128 v[184:187], v242 offset:37888
	ds_read_b128 v[164:167], v242 offset:38912
	ds_read_b128 v[180:183], v242 offset:39936
	global_load_lds_dwordx4 v[196:197], off
	v_lshl_add_u64 v[196:197], s[20:21], 0, v[210:211]
	s_mov_b32 m0, s60
	s_nop 0
	global_load_lds_dwordx4 v[196:197], off
	s_waitcnt vmcnt(8)
	s_waitcnt lgkmcnt(0)
	s_barrier
	s_setprio 1
	s_waitcnt lgkmcnt(0)
	v_mfma_f32_16x16x32_bf16 v[128:131], v[148:151], v[176:179], v[128:131]
	v_mfma_f32_16x16x32_bf16 v[124:127], v[156:159], v[176:179], v[124:127]
	v_mfma_f32_16x16x32_bf16 v[112:115], v[148:151], v[172:175], v[112:115]
	v_mfma_f32_16x16x32_bf16 v[108:111], v[156:159], v[172:175], v[108:111]
	v_mfma_f32_16x16x32_bf16 v[96:99], v[148:151], v[168:171], v[96:99]
	v_mfma_f32_16x16x32_bf16 v[92:95], v[156:159], v[168:171], v[92:95]
	v_mfma_f32_16x16x32_bf16 v[80:83], v[148:151], v[164:167], v[80:83]
	v_mfma_f32_16x16x32_bf16 v[76:79], v[156:159], v[164:167], v[76:79]
	v_mfma_f32_16x16x32_bf16 v[128:131], v[152:155], v[192:195], v[128:131]
	v_mfma_f32_16x16x32_bf16 v[124:127], v[160:163], v[192:195], v[124:127]
	v_mfma_f32_16x16x32_bf16 v[112:115], v[152:155], v[188:191], v[112:115]
	v_mfma_f32_16x16x32_bf16 v[108:111], v[160:163], v[188:191], v[108:111]
	v_mfma_f32_16x16x32_bf16 v[96:99], v[152:155], v[184:187], v[96:99]
	v_mfma_f32_16x16x32_bf16 v[92:95], v[160:163], v[184:187], v[92:95]
	v_mfma_f32_16x16x32_bf16 v[80:83], v[152:155], v[180:183], v[80:83]
	v_mfma_f32_16x16x32_bf16 v[76:79], v[160:163], v[180:183], v[76:79]
	s_setprio 0
	s_setprio 1
	v_mfma_f32_16x16x32_bf16 v[120:123], v[132:135], v[176:179], v[120:123]
	v_mfma_f32_16x16x32_bf16 v[116:119], v[140:143], v[176:179], v[116:119]
	v_mfma_f32_16x16x32_bf16 v[104:107], v[132:135], v[172:175], v[104:107]
	v_mfma_f32_16x16x32_bf16 v[100:103], v[140:143], v[172:175], v[100:103]
	v_mfma_f32_16x16x32_bf16 v[88:91], v[132:135], v[168:171], v[88:91]
	v_mfma_f32_16x16x32_bf16 v[84:87], v[140:143], v[168:171], v[84:87]
	v_mfma_f32_16x16x32_bf16 v[72:75], v[132:135], v[164:167], v[72:75]
	v_mfma_f32_16x16x32_bf16 v[68:71], v[140:143], v[164:167], v[68:71]
	v_mfma_f32_16x16x32_bf16 v[120:123], v[136:139], v[192:195], v[120:123]
	v_mfma_f32_16x16x32_bf16 v[116:119], v[144:147], v[192:195], v[116:119]
	v_mfma_f32_16x16x32_bf16 v[104:107], v[136:139], v[188:191], v[104:107]
	v_mfma_f32_16x16x32_bf16 v[100:103], v[144:147], v[188:191], v[100:103]
	v_mfma_f32_16x16x32_bf16 v[88:91], v[136:139], v[184:187], v[88:91]
	v_mfma_f32_16x16x32_bf16 v[84:87], v[144:147], v[184:187], v[84:87]
	v_mfma_f32_16x16x32_bf16 v[72:75], v[136:139], v[180:183], v[72:75]
	v_mfma_f32_16x16x32_bf16 v[68:71], v[144:147], v[180:183], v[68:71]
	s_setprio 0
	s_barrier
	s_and_b64 vcc, exec, s[40:41]
	s_cbranch_vccnz .LBB0_687
	ds_read_b128 v[176:179], v242 offset:49152
	ds_read_b128 v[192:195], v242 offset:50176
	ds_read_b128 v[172:175], v242 offset:51200
	ds_read_b128 v[188:191], v242 offset:52224
	ds_read_b128 v[168:171], v242 offset:53248
	ds_read_b128 v[184:187], v242 offset:54272
	ds_read_b128 v[164:167], v242 offset:55296
	ds_read_b128 v[180:183], v242 offset:56320
